# bias table build: ten loads per thread issued together (P2 and P3 sample attention)
# speedup vs baseline: 1.0111x; 1.0007x over previous
.LBB0_669:
	s_or_b64 exec, exec, s[0:1]
	s_mov_b64 s[0:1], s[62:63]
	s_mov_b64 s[8:9], s[60:61]
	s_waitcnt lgkmcnt(0)
	s_barrier
	v_readlane_b32 s98, v245, 4
	v_readlane_b32 s99, v245, 5
	s_mov_b32 s100, 0x66666667
	v_mov_b32_e32 v21, 0x280
	v_mov_b32_e32 v22, 0x201
	v_mov_b32_e32 v23, 0xffffff00
	v_mov_b32_e32 v24, 0x100
	v_add_u32_e32 v1, 0, v220
	v_mul_hi_u32 v2, v1, s100
	v_lshrrev_b32_e32 v2, 8, v2
	v_sub_u32_e32 v3, 0x240, v1
	v_mad_i32_i24 v3, v2, v21, v3
	v_med3_i32 v3, v3, v23, v24
	v_mad_i32_i24 v3, v2, v22, v3
	v_add_u32_e32 v3, 0x100, v3
	v_lshlrev_b32_e32 v3, 2, v3
	global_load_dword v5, v3, s[98:99]
	v_add_u32_e32 v1, 512, v220
	v_mul_hi_u32 v2, v1, s100
	v_lshrrev_b32_e32 v2, 8, v2
	v_sub_u32_e32 v3, 0x240, v1
	v_mad_i32_i24 v3, v2, v21, v3
	v_med3_i32 v3, v3, v23, v24
	v_mad_i32_i24 v3, v2, v22, v3
	v_add_u32_e32 v3, 0x100, v3
	v_lshlrev_b32_e32 v3, 2, v3
	global_load_dword v6, v3, s[98:99]
	v_add_u32_e32 v1, 1024, v220
	v_mul_hi_u32 v2, v1, s100
	v_lshrrev_b32_e32 v2, 8, v2
	v_sub_u32_e32 v3, 0x240, v1
	v_mad_i32_i24 v3, v2, v21, v3
	v_med3_i32 v3, v3, v23, v24
	v_mad_i32_i24 v3, v2, v22, v3
	v_add_u32_e32 v3, 0x100, v3
	v_lshlrev_b32_e32 v3, 2, v3
	global_load_dword v7, v3, s[98:99]
	v_add_u32_e32 v1, 1536, v220
	v_mul_hi_u32 v2, v1, s100
	v_lshrrev_b32_e32 v2, 8, v2
	v_sub_u32_e32 v3, 0x240, v1
	v_mad_i32_i24 v3, v2, v21, v3
	v_med3_i32 v3, v3, v23, v24
	v_mad_i32_i24 v3, v2, v22, v3
	v_add_u32_e32 v3, 0x100, v3
	v_lshlrev_b32_e32 v3, 2, v3
	global_load_dword v8, v3, s[98:99]
	v_add_u32_e32 v1, 2048, v220
	v_mul_hi_u32 v2, v1, s100
	v_lshrrev_b32_e32 v2, 8, v2
	v_sub_u32_e32 v3, 0x240, v1
	v_mad_i32_i24 v3, v2, v21, v3
	v_med3_i32 v3, v3, v23, v24
	v_mad_i32_i24 v3, v2, v22, v3
	v_add_u32_e32 v3, 0x100, v3
	v_lshlrev_b32_e32 v3, 2, v3
	global_load_dword v9, v3, s[98:99]
	v_add_u32_e32 v1, 2560, v220
	v_mul_hi_u32 v2, v1, s100
	v_lshrrev_b32_e32 v2, 8, v2
	v_sub_u32_e32 v3, 0x240, v1
	v_mad_i32_i24 v3, v2, v21, v3
	v_med3_i32 v3, v3, v23, v24
	v_mad_i32_i24 v3, v2, v22, v3
	v_add_u32_e32 v3, 0x100, v3
	v_lshlrev_b32_e32 v3, 2, v3
	global_load_dword v10, v3, s[98:99]
	v_add_u32_e32 v1, 3072, v220
	v_mul_hi_u32 v2, v1, s100
	v_lshrrev_b32_e32 v2, 8, v2
	v_sub_u32_e32 v3, 0x240, v1
	v_mad_i32_i24 v3, v2, v21, v3
	v_med3_i32 v3, v3, v23, v24
	v_mad_i32_i24 v3, v2, v22, v3
	v_add_u32_e32 v3, 0x100, v3
	v_lshlrev_b32_e32 v3, 2, v3
	global_load_dword v11, v3, s[98:99]
	v_add_u32_e32 v1, 3584, v220
	v_mul_hi_u32 v2, v1, s100
	v_lshrrev_b32_e32 v2, 8, v2
	v_sub_u32_e32 v3, 0x240, v1
	v_mad_i32_i24 v3, v2, v21, v3
	v_med3_i32 v3, v3, v23, v24
	v_mad_i32_i24 v3, v2, v22, v3
	v_add_u32_e32 v3, 0x100, v3
	v_lshlrev_b32_e32 v3, 2, v3
	global_load_dword v12, v3, s[98:99]
	v_add_u32_e32 v1, 4096, v220
	v_mul_hi_u32 v2, v1, s100
	v_lshrrev_b32_e32 v2, 8, v2
	v_sub_u32_e32 v3, 0x240, v1
	v_mad_i32_i24 v3, v2, v21, v3
	v_med3_i32 v3, v3, v23, v24
	v_mad_i32_i24 v3, v2, v22, v3
	v_add_u32_e32 v3, 0x100, v3
	v_lshlrev_b32_e32 v3, 2, v3
	global_load_dword v13, v3, s[98:99]
	v_add_u32_e32 v1, 4608, v220
	v_mul_hi_u32 v2, v1, s100
	v_lshrrev_b32_e32 v2, 8, v2
	v_sub_u32_e32 v3, 0x240, v1
	v_mad_i32_i24 v3, v2, v21, v3
	v_med3_i32 v3, v3, v23, v24
	v_mad_i32_i24 v3, v2, v22, v3
	v_add_u32_e32 v3, 0x100, v3
	v_lshlrev_b32_e32 v3, 2, v3
	global_load_dword v14, v3, s[98:99]
	v_lshlrev_b32_e32 v4, 2, v220
	s_waitcnt vmcnt(0)
	v_mul_f32_e32 v5, 0x3fb8aa3b, v5
	ds_write_b32 v4, v5
	v_mul_f32_e32 v6, 0x3fb8aa3b, v6
	ds_write_b32 v4, v6 offset:2048
	v_mul_f32_e32 v7, 0x3fb8aa3b, v7
	ds_write_b32 v4, v7 offset:4096
	v_mul_f32_e32 v8, 0x3fb8aa3b, v8
	ds_write_b32 v4, v8 offset:6144
	v_mul_f32_e32 v9, 0x3fb8aa3b, v9
	ds_write_b32 v4, v9 offset:8192
	v_mul_f32_e32 v10, 0x3fb8aa3b, v10
	ds_write_b32 v4, v10 offset:10240
	v_mul_f32_e32 v11, 0x3fb8aa3b, v11
	ds_write_b32 v4, v11 offset:12288
	v_mul_f32_e32 v12, 0x3fb8aa3b, v12
	ds_write_b32 v4, v12 offset:14336
	v_mul_f32_e32 v13, 0x3fb8aa3b, v13
	ds_write_b32 v4, v13 offset:16384
	v_mul_f32_e32 v14, 0x3fb8aa3b, v14
	ds_write_b32 v4, v14 offset:18432
	v_mov_b32_e32 v2, v220
	s_movk_i32 s8, 0
	s_nop 0
	v_readfirstlane_b32 s20, v2
	v_cmp_gt_i32_e32 vcc, s8, v2
	s_and_saveexec_b64 s[8:9], vcc
	v_readlane_b32 s68, v245, 0
	s_mov_b64 s[16:17], s[84:85]
	v_readlane_b32 s69, v245, 1
	v_readlane_b32 s70, v245, 2
	v_readlane_b32 s71, v245, 3
	v_readlane_b32 s72, v245, 4
	v_readlane_b32 s73, v245, 5
	v_readlane_b32 s74, v245, 6
	v_readlane_b32 s75, v245, 7
	v_readlane_b32 s76, v245, 8
	v_readlane_b32 s77, v245, 9
	v_readlane_b32 s78, v245, 10
	v_readlane_b32 s79, v245, 11
	v_readlane_b32 s80, v245, 12
	v_readlane_b32 s81, v245, 13
	v_readlane_b32 s82, v245, 14
	v_readlane_b32 s83, v245, 15
	s_cbranch_execz .LBB0_681
	v_max_i32_e32 v0, 0x1200, v2
	v_sub_u32_e32 v0, v0, v2
	s_movk_i32 s10, 0x1ff
	v_add_u32_e32 v1, 0x1ff, v0
	v_cmp_lt_u32_e32 vcc, s10, v1
	s_mov_b64 s[38:39], -1
	v_mov_b32_e32 v0, v2
	s_and_saveexec_b64 s[10:11], vcc
	s_cbranch_execz .LBB0_678
	v_lshrrev_b32_e32 v4, 9, v1
	v_add_u32_e32 v3, 0x200, v2
	v_add_u32_e32 v5, -1, v4
	v_cmp_lt_u32_e32 vcc, 1, v5
	v_mov_b32_e32 v6, 0
	v_mov_b64_e32 v[0:1], v[2:3]
	s_and_saveexec_b64 s[38:39], vcc
	s_cbranch_execz .LBB0_675
	v_lshrrev_b32_e32 v0, 1, v5
	v_readlane_b32 s68, v245, 0
	v_add_u32_e32 v0, 1, v0
	v_readlane_b32 s72, v245, 4
	v_readlane_b32 s73, v245, 5
	v_and_b32_e32 v6, -2, v0
	s_mov_b32 s21, 0
	v_lshl_add_u32 v7, v2, 2, 0
	s_mov_b64 s[40:41], 0
	s_mov_b32 s22, 0x66666667
	s_movk_i32 s23, 0x280
	s_movk_i32 s33, 0xff00
	v_mov_b32_e32 v8, 0x100
	s_movk_i32 s43, 0x201
	s_mov_b32 s42, 0x3fb8aa3b
	v_mov_b64_e32 v[0:1], v[2:3]
	s_mov_b64 s[48:49], s[72:73]
	v_readlane_b32 s69, v245, 1
	v_readlane_b32 s70, v245, 2
	v_readlane_b32 s71, v245, 3
	v_readlane_b32 s74, v245, 6
	v_readlane_b32 s75, v245, 7
	v_readlane_b32 s76, v245, 8
	v_readlane_b32 s77, v245, 9
	v_readlane_b32 s78, v245, 10
	v_readlane_b32 s79, v245, 11
	v_readlane_b32 s80, v245, 12
	v_readlane_b32 s81, v245, 13
	v_readlane_b32 s82, v245, 14
	v_readlane_b32 s83, v245, 15

.LBB0_765:
	s_andn2_b64 vcc, exec, s[8:9]
	s_cbranch_vccnz .LBB0_784
	v_readlane_b32 s98, v245, 4
	v_readlane_b32 s99, v245, 5
	s_mov_b32 s100, 0x66666667
	v_mov_b32_e32 v21, 0x280
	v_mov_b32_e32 v22, 0x201
	v_mov_b32_e32 v23, 0xffffff00
	v_mov_b32_e32 v24, 0x100
	v_add_u32_e32 v1, 0, v220
	v_mul_hi_u32 v2, v1, s100
	v_lshrrev_b32_e32 v2, 8, v2
	v_sub_u32_e32 v3, 0x240, v1
	v_mad_i32_i24 v3, v2, v21, v3
	v_med3_i32 v3, v3, v23, v24
	v_mad_i32_i24 v3, v2, v22, v3
	v_add_u32_e32 v3, 0x100, v3
	v_lshlrev_b32_e32 v3, 2, v3
	global_load_dword v5, v3, s[98:99]
	v_add_u32_e32 v1, 512, v220
	v_mul_hi_u32 v2, v1, s100
	v_lshrrev_b32_e32 v2, 8, v2
	v_sub_u32_e32 v3, 0x240, v1
	v_mad_i32_i24 v3, v2, v21, v3
	v_med3_i32 v3, v3, v23, v24
	v_mad_i32_i24 v3, v2, v22, v3
	v_add_u32_e32 v3, 0x100, v3
	v_lshlrev_b32_e32 v3, 2, v3
	global_load_dword v6, v3, s[98:99]
	v_add_u32_e32 v1, 1024, v220
	v_mul_hi_u32 v2, v1, s100
	v_lshrrev_b32_e32 v2, 8, v2
	v_sub_u32_e32 v3, 0x240, v1
	v_mad_i32_i24 v3, v2, v21, v3
	v_med3_i32 v3, v3, v23, v24
	v_mad_i32_i24 v3, v2, v22, v3
	v_add_u32_e32 v3, 0x100, v3
	v_lshlrev_b32_e32 v3, 2, v3
	global_load_dword v7, v3, s[98:99]
	v_add_u32_e32 v1, 1536, v220
	v_mul_hi_u32 v2, v1, s100
	v_lshrrev_b32_e32 v2, 8, v2
	v_sub_u32_e32 v3, 0x240, v1
	v_mad_i32_i24 v3, v2, v21, v3
	v_med3_i32 v3, v3, v23, v24
	v_mad_i32_i24 v3, v2, v22, v3
	v_add_u32_e32 v3, 0x100, v3
	v_lshlrev_b32_e32 v3, 2, v3
	global_load_dword v8, v3, s[98:99]
	v_add_u32_e32 v1, 2048, v220
	v_mul_hi_u32 v2, v1, s100
	v_lshrrev_b32_e32 v2, 8, v2
	v_sub_u32_e32 v3, 0x240, v1
	v_mad_i32_i24 v3, v2, v21, v3
	v_med3_i32 v3, v3, v23, v24
	v_mad_i32_i24 v3, v2, v22, v3
	v_add_u32_e32 v3, 0x100, v3
	v_lshlrev_b32_e32 v3, 2, v3
	global_load_dword v9, v3, s[98:99]
	v_add_u32_e32 v1, 2560, v220
	v_mul_hi_u32 v2, v1, s100
	v_lshrrev_b32_e32 v2, 8, v2
	v_sub_u32_e32 v3, 0x240, v1
	v_mad_i32_i24 v3, v2, v21, v3
	v_med3_i32 v3, v3, v23, v24
	v_mad_i32_i24 v3, v2, v22, v3
	v_add_u32_e32 v3, 0x100, v3
	v_lshlrev_b32_e32 v3, 2, v3
	global_load_dword v10, v3, s[98:99]
	v_add_u32_e32 v1, 3072, v220
	v_mul_hi_u32 v2, v1, s100
	v_lshrrev_b32_e32 v2, 8, v2
	v_sub_u32_e32 v3, 0x240, v1
	v_mad_i32_i24 v3, v2, v21, v3
	v_med3_i32 v3, v3, v23, v24
	v_mad_i32_i24 v3, v2, v22, v3
	v_add_u32_e32 v3, 0x100, v3
	v_lshlrev_b32_e32 v3, 2, v3
	global_load_dword v11, v3, s[98:99]
	v_add_u32_e32 v1, 3584, v220
	v_mul_hi_u32 v2, v1, s100
	v_lshrrev_b32_e32 v2, 8, v2
	v_sub_u32_e32 v3, 0x240, v1
	v_mad_i32_i24 v3, v2, v21, v3
	v_med3_i32 v3, v3, v23, v24
	v_mad_i32_i24 v3, v2, v22, v3
	v_add_u32_e32 v3, 0x100, v3
	v_lshlrev_b32_e32 v3, 2, v3
	global_load_dword v12, v3, s[98:99]
	v_add_u32_e32 v1, 4096, v220
	v_mul_hi_u32 v2, v1, s100
	v_lshrrev_b32_e32 v2, 8, v2
	v_sub_u32_e32 v3, 0x240, v1
	v_mad_i32_i24 v3, v2, v21, v3
	v_med3_i32 v3, v3, v23, v24
	v_mad_i32_i24 v3, v2, v22, v3
	v_add_u32_e32 v3, 0x100, v3
	v_lshlrev_b32_e32 v3, 2, v3
	global_load_dword v13, v3, s[98:99]
	v_add_u32_e32 v1, 4608, v220
	v_mul_hi_u32 v2, v1, s100
	v_lshrrev_b32_e32 v2, 8, v2
	v_sub_u32_e32 v3, 0x240, v1
	v_mad_i32_i24 v3, v2, v21, v3
	v_med3_i32 v3, v3, v23, v24
	v_mad_i32_i24 v3, v2, v22, v3
	v_add_u32_e32 v3, 0x100, v3
	v_lshlrev_b32_e32 v3, 2, v3
	global_load_dword v14, v3, s[98:99]
	v_lshlrev_b32_e32 v4, 2, v220
	s_waitcnt vmcnt(0)
	v_mul_f32_e32 v5, 0x3fb8aa3b, v5
	ds_write_b32 v4, v5
	v_mul_f32_e32 v6, 0x3fb8aa3b, v6
	ds_write_b32 v4, v6 offset:2048
	v_mul_f32_e32 v7, 0x3fb8aa3b, v7
	ds_write_b32 v4, v7 offset:4096
	v_mul_f32_e32 v8, 0x3fb8aa3b, v8
	ds_write_b32 v4, v8 offset:6144
	v_mul_f32_e32 v9, 0x3fb8aa3b, v9
	ds_write_b32 v4, v9 offset:8192
	v_mul_f32_e32 v10, 0x3fb8aa3b, v10
	ds_write_b32 v4, v10 offset:10240
	v_mul_f32_e32 v11, 0x3fb8aa3b, v11
	ds_write_b32 v4, v11 offset:12288
	v_mul_f32_e32 v12, 0x3fb8aa3b, v12
	ds_write_b32 v4, v12 offset:14336
	v_mul_f32_e32 v13, 0x3fb8aa3b, v13
	ds_write_b32 v4, v13 offset:16384
	v_mul_f32_e32 v14, 0x3fb8aa3b, v14
	ds_write_b32 v4, v14 offset:18432
	s_movk_i32 s8, 0
	v_cmp_gt_i32_e32 vcc, s8, v96
	s_and_saveexec_b64 s[8:9], vcc
	v_readlane_b32 s68, v245, 0
	v_readlane_b32 s69, v245, 1
	v_readlane_b32 s70, v245, 2
	v_readlane_b32 s71, v245, 3
	v_readlane_b32 s72, v245, 4
	v_readlane_b32 s73, v245, 5
	v_readlane_b32 s74, v245, 6
	v_readlane_b32 s75, v245, 7
	v_readlane_b32 s76, v245, 8
	v_readlane_b32 s77, v245, 9
	v_readlane_b32 s78, v245, 10
	v_readlane_b32 s79, v245, 11
	v_readlane_b32 s80, v245, 12
	v_readlane_b32 s81, v245, 13
	v_readlane_b32 s82, v245, 14
	v_readlane_b32 s83, v245, 15
	s_cbranch_execz .LBB0_778
	v_max_i32_e32 v1, 0x1200, v96
	v_sub_u32_e32 v1, v1, v96
	s_movk_i32 s10, 0x1ff
	v_add_u32_e32 v2, 0x1ff, v1
	v_cmp_lt_u32_e32 vcc, s10, v2
	s_mov_b64 s[14:15], -1
	v_mov_b32_e32 v1, v96
	s_and_saveexec_b64 s[10:11], vcc
	s_cbranch_execz .LBB0_775
	v_lshrrev_b32_e32 v1, 9, v2
	v_add_u32_e32 v97, 0x200, v96
	v_add_u32_e32 v4, -1, v1
	v_cmp_lt_u32_e32 vcc, 1, v4
	v_mov_b32_e32 v5, 0
	v_mov_b64_e32 v[2:3], v[96:97]
	s_and_saveexec_b64 s[14:15], vcc
	s_cbranch_execz .LBB0_772
	v_lshrrev_b32_e32 v2, 1, v4
	v_add_u32_e32 v2, 1, v2
	v_readlane_b32 s72, v245, 0
	v_and_b32_e32 v5, -2, v2
	s_mov_b32 s23, 0
	v_lshl_add_u32 v6, v96, 2, 0
	s_mov_b64 s[40:41], 0
	s_mov_b32 s33, 0x66666667
	s_movk_i32 s43, 0x280
	s_movk_i32 s44, 0xff00
	v_mov_b32_e32 v7, 0x100
	s_movk_i32 s45, 0x201
	s_mov_b32 s42, 0x3fb8aa3b
	v_mov_b64_e32 v[2:3], v[96:97]
	v_readlane_b32 s76, v245, 4
	v_readlane_b32 s77, v245, 5
	v_readlane_b32 s73, v245, 1
	v_readlane_b32 s74, v245, 2
	v_readlane_b32 s75, v245, 3
	v_readlane_b32 s78, v245, 6
	v_readlane_b32 s79, v245, 7
	v_readlane_b32 s80, v245, 8
	v_readlane_b32 s81, v245, 9
	v_readlane_b32 s82, v245, 10
	v_readlane_b32 s83, v245, 11
	v_readlane_b32 s84, v245, 12
	v_readlane_b32 s85, v245, 13
	v_readlane_b32 s86, v245, 14
	v_readlane_b32 s87, v245, 15
